# attention-A softmax v_pk_add_f32 split into scalar v_add_f32 pairs (both A-loop copies)
# speedup vs baseline: 1.0000x; 1.0000x over previous
.LBB0_209:
	s_mulk_i32 s21, 0x3c00
	s_mul_hi_u32 s37, s20, 0x3c00
	s_add_i32 s49, s49, 1
	s_add_i32 s37, s37, s21
	s_mulk_i32 s20, 0x3c00
	s_add_u32 s20, s30, s20
	s_addc_u32 s21, s53, s37
	s_lshl_b64 s[42:43], s[42:43], 1
	s_add_u32 s42, s62, s42
	s_addc_u32 s43, s63, s43
	s_lshl_b32 s37, s64, 14
	s_add_i32 s39, s37, 0xffffc000
	s_cmp_lg_u32 s64, 0
	s_cselect_b32 s39, s39, 0x8000
	v_lshl_add_u64 v[88:89], v[176:177], 1, s[20:21]
	s_mov_b64 s[4:5], 0x400
	s_add_i32 s39, s59, s39
	v_lshl_add_u64 v[88:89], v[88:89], 0, s[4:5]
	s_mov_b32 m0, s39
	s_nop 0
	global_load_lds_dwordx4 v[88:89], off
	v_lshl_add_u64 v[88:89], v[160:161], 1, s[42:43]
	s_add_i32 m0, s39, 0xc000
	s_nop 0
	global_load_lds_dwordx4 v[88:89], off
	v_lshl_add_u64 v[88:89], v[162:163], 1, s[20:21]
	v_lshl_add_u64 v[88:89], v[88:89], 0, s[4:5]
	s_add_i32 m0, s39, 0x400
	s_add_i32 s20, s37, 0
	global_load_lds_dwordx4 v[88:89], off
	v_lshl_add_u64 v[88:89], v[164:165], 1, s[42:43]
	s_add_i32 m0, s39, 0xc400
	s_add_i32 s20, s46, s20
	global_load_lds_dwordx4 v[88:89], off
	v_add3_u32 v100, s20, v210, v166
	v_add3_u32 v116, s20, v209, v166
	ds_read_b128 v[88:91], v100
	ds_read_b128 v[92:95], v100 offset:2048
	ds_read_b128 v[96:99], v100 offset:4096
	ds_read_b128 v[100:103], v100 offset:6144
	ds_read_b128 v[104:107], v116
	ds_read_b128 v[108:111], v116 offset:2048
	ds_read_b128 v[112:115], v116 offset:4096
	ds_read_b128 v[116:119], v116 offset:6144
	s_waitcnt lgkmcnt(0)
	v_mfma_f32_16x16x32_bf16 v[120:123], v[88:91], v[4:7], v[16:19]
	v_mfma_f32_16x16x32_bf16 v[88:91], v[88:91], v[12:15], v[20:23]
	v_mfma_f32_16x16x32_bf16 v[124:127], v[92:95], v[4:7], v[16:19]
	v_mfma_f32_16x16x32_bf16 v[92:95], v[92:95], v[12:15], v[20:23]
	v_mfma_f32_16x16x32_bf16 v[128:131], v[96:99], v[4:7], v[16:19]
	v_mfma_f32_16x16x32_bf16 v[96:99], v[96:99], v[12:15], v[20:23]
	v_mfma_f32_16x16x32_bf16 v[132:135], v[100:103], v[4:7], v[16:19]
	v_mfma_f32_16x16x32_bf16 v[100:103], v[100:103], v[12:15], v[20:23]
	v_mfma_f32_16x16x32_bf16 v[172:175], v[104:107], v[8:11], v[88:91]
	s_nop 2
	v_add_u32_e32 v88, s37, v167
	v_mfma_f32_16x16x32_bf16 v[212:215], v[108:111], v[8:11], v[92:95]
	v_add_u32_e32 v89, v88, v210
	ds_read_b128 v[152:155], v89 offset:49152
	s_nop 0
	v_add_u32_e32 v92, v88, v209
	v_mfma_f32_16x16x32_bf16 v[168:171], v[104:107], v[0:3], v[120:123]
	v_mfma_f32_16x16x32_bf16 v[104:107], v[108:111], v[0:3], v[124:127]
	v_mfma_f32_16x16x32_bf16 v[216:219], v[112:115], v[0:3], v[128:131]
	v_mfma_f32_16x16x32_bf16 v[220:223], v[112:115], v[8:11], v[96:99]
	v_mfma_f32_16x16x32_bf16 v[224:227], v[116:119], v[0:3], v[132:135]
	v_mfma_f32_16x16x32_bf16 v[228:231], v[116:119], v[8:11], v[100:103]
	ds_read_b128 v[112:115], v92 offset:49152
	ds_read_b128 v[116:119], v89 offset:51200
	ds_read_b128 v[120:123], v92 offset:51200
	ds_read_b128 v[128:131], v89 offset:53248
	ds_read_b128 v[124:127], v92 offset:53248
	ds_read_b128 v[132:135], v89 offset:55296
	ds_read_b128 v[136:139], v92 offset:55296
	ds_read_b128 v[144:147], v89 offset:57344
	ds_read_b128 v[140:143], v92 offset:57344
	ds_read_b128 v[156:159], v89 offset:59392
	ds_read_b128 v[148:151], v92 offset:59392
	ds_read_b128 v[108:111], v89 offset:61440
	ds_read_b128 v[96:99], v92 offset:61440
	ds_read_b128 v[88:91], v89 offset:63488
	ds_read_b128 v[92:95], v92 offset:63488
	v_exp_f32_e32 v233, v168
	v_exp_f32_e32 v232, v172
	v_exp_f32_e32 v235, v104
	v_exp_f32_e32 v237, v216
	v_exp_f32_e32 v239, v224
	v_exp_f32_e32 v169, v169
	v_exp_f32_e32 v234, v212
	v_exp_f32_e32 v236, v220
	v_exp_f32_e32 v238, v228
	v_exp_f32_e32 v168, v173
	v_exp_f32_e32 v241, v105
	v_exp_f32_e32 v217, v217
	v_exp_f32_e32 v225, v225
	v_exp_f32_e32 v243, v170
	v_exp_f32_e32 v240, v213
	v_exp_f32_e32 v216, v221
	v_exp_f32_e32 v224, v229
	v_exp_f32_e32 v242, v174
	v_exp_f32_e32 v245, v106
	v_exp_f32_e32 v247, v218
	v_exp_f32_e32 v249, v226
	v_exp_f32_e32 v171, v171
	v_exp_f32_e32 v251, v107
	v_exp_f32_e32 v244, v214
	v_exp_f32_e32 v246, v222
	v_exp_f32_e32 v248, v230
	v_exp_f32_e32 v170, v175
	v_exp_f32_e32 v250, v215
	v_exp_f32_e32 v219, v219
	v_exp_f32_e32 v227, v227
	v_exp_f32_e32 v218, v223
	v_exp_f32_e32 v226, v231
	v_add_f32_e32 v172, 0, v232
	v_add_f32_e32 v173, 0, v233
	v_add_f32_e32 v174, 0, v234
	v_add_f32_e32 v175, 0, v235
	v_add_f32_e32 v212, 0, v236
	v_add_f32_e32 v213, 0, v237
	v_add_f32_e32 v214, 0, v238
	v_add_f32_e32 v215, 0, v239
	v_add_f32_e32 v172, v168, v172
	v_add_f32_e32 v173, v169, v173
	v_add_f32_e32 v174, v240, v174
	v_add_f32_e32 v175, v241, v175
	v_add_f32_e32 v212, v216, v212
	v_add_f32_e32 v213, v217, v213
	v_add_f32_e32 v214, v224, v214
	v_add_f32_e32 v215, v225, v215
	v_add_f32_e32 v172, v242, v172
	v_add_f32_e32 v173, v243, v173
	v_cvt_pk_bf16_f32 v104, v233, v169
	v_cvt_pk_bf16_f32 v105, v243, v171
	v_cvt_pk_bf16_f32 v106, v235, v241
	v_cvt_pk_bf16_f32 v107, v245, v251
	v_add_f32_e32 v174, v244, v174
	v_add_f32_e32 v175, v245, v175
	v_add_f32_e32 v212, v246, v212
	v_add_f32_e32 v213, v247, v213
	v_add_f32_e32 v214, v248, v214
	v_add_f32_e32 v215, v249, v215
	v_add_f32_e32 v172, v170, v172
	v_add_f32_e32 v173, v171, v173
	v_cvt_pk_bf16_f32 v168, v232, v168
	v_cvt_pk_bf16_f32 v169, v242, v170
	v_cvt_pk_bf16_f32 v170, v234, v240
	v_cvt_pk_bf16_f32 v171, v244, v250
	v_add_f32_e32 v174, v250, v174
	v_add_f32_e32 v175, v251, v175
	v_add_f32_e32 v212, v218, v212
	v_add_f32_e32 v213, v219, v213
	v_add_f32_e32 v214, v226, v214
	v_add_f32_e32 v215, v227, v215
	s_waitcnt lgkmcnt(0)
	v_mfma_f32_16x16x32_bf16 v[84:87], v[152:155], v[104:107], v[84:87]
	v_add_f32_e64 v172, v172, v174
	v_add_f32_e64 v173, v173, v175
	v_add_f32_e32 v174, v212, v214
	v_add_f32_e32 v175, v213, v215
	v_cvt_pk_bf16_f32 v100, v237, v217
	v_mfma_f32_16x16x32_bf16 v[80:83], v[152:155], v[168:171], v[80:83]
	v_add_f32_e64 v172, v172, v174
	v_add_f32_e64 v173, v173, v175
	v_cvt_pk_bf16_f32 v101, v247, v219
	v_cvt_pk_bf16_f32 v102, v239, v225
	v_mfma_f32_16x16x32_bf16 v[76:79], v[116:119], v[104:107], v[76:79]
	v_cvt_pk_bf16_f32 v103, v249, v227
	v_add_f32_e32 v182, v182, v172
	v_add_f32_e32 v183, v183, v173
	v_cvt_pk_bf16_f32 v172, v236, v216
	v_mfma_f32_16x16x32_bf16 v[72:75], v[116:119], v[168:171], v[72:75]
	v_cvt_pk_bf16_f32 v173, v246, v218
	v_cvt_pk_bf16_f32 v174, v238, v224
	v_cvt_pk_bf16_f32 v175, v248, v226
	v_mfma_f32_16x16x32_bf16 v[68:71], v[128:131], v[104:107], v[68:71]
	s_add_i32 s20, s64, 1
	s_cmp_lg_u32 s64, 2
	s_cselect_b32 s64, s20, 0
	v_mfma_f32_16x16x32_bf16 v[64:67], v[128:131], v[168:171], v[64:67]
	s_add_u32 s40, s40, 64
	s_addc_u32 s41, s41, 0
	s_cmp_eq_u32 s49, 34
	v_mfma_f32_16x16x32_bf16 v[60:63], v[132:135], v[104:107], v[60:63]
	v_mfma_f32_16x16x32_bf16 v[56:59], v[132:135], v[168:171], v[56:59]
	v_mfma_f32_16x16x32_bf16 v[52:55], v[144:147], v[104:107], v[52:55]
	v_mfma_f32_16x16x32_bf16 v[48:51], v[144:147], v[168:171], v[48:51]
	v_mfma_f32_16x16x32_bf16 v[44:47], v[156:159], v[104:107], v[44:47]
	v_mfma_f32_16x16x32_bf16 v[40:43], v[156:159], v[168:171], v[40:43]
	v_mfma_f32_16x16x32_bf16 v[36:39], v[108:111], v[104:107], v[36:39]
	v_mfma_f32_16x16x32_bf16 v[24:27], v[108:111], v[168:171], v[24:27]
	v_mfma_f32_16x16x32_bf16 v[32:35], v[88:91], v[104:107], v[32:35]
	v_mfma_f32_16x16x32_bf16 v[28:31], v[88:91], v[168:171], v[28:31]
	v_mfma_f32_16x16x32_bf16 v[84:87], v[112:115], v[100:103], v[84:87]
	v_mfma_f32_16x16x32_bf16 v[80:83], v[112:115], v[172:175], v[80:83]
	v_mfma_f32_16x16x32_bf16 v[76:79], v[120:123], v[100:103], v[76:79]
	v_mfma_f32_16x16x32_bf16 v[72:75], v[120:123], v[172:175], v[72:75]
	v_mfma_f32_16x16x32_bf16 v[68:71], v[124:127], v[100:103], v[68:71]
	v_mfma_f32_16x16x32_bf16 v[64:67], v[124:127], v[172:175], v[64:67]
	v_mfma_f32_16x16x32_bf16 v[60:63], v[136:139], v[100:103], v[60:63]
	v_mfma_f32_16x16x32_bf16 v[56:59], v[136:139], v[172:175], v[56:59]
	v_mfma_f32_16x16x32_bf16 v[52:55], v[140:143], v[100:103], v[52:55]
	v_mfma_f32_16x16x32_bf16 v[48:51], v[140:143], v[172:175], v[48:51]
	v_mfma_f32_16x16x32_bf16 v[44:47], v[148:151], v[100:103], v[44:47]
	v_mfma_f32_16x16x32_bf16 v[40:43], v[148:151], v[172:175], v[40:43]
	v_mfma_f32_16x16x32_bf16 v[36:39], v[96:99], v[100:103], v[36:39]
	v_mfma_f32_16x16x32_bf16 v[24:27], v[96:99], v[172:175], v[24:27]
	v_mfma_f32_16x16x32_bf16 v[32:35], v[92:95], v[100:103], v[32:35]
	v_mfma_f32_16x16x32_bf16 v[28:31], v[92:95], v[172:175], v[28:31]
	s_cbranch_scc1 .LBB0_214

.LBB0_749:
	s_mulk_i32 s21, 0x3c00
	s_mul_hi_u32 s37, s20, 0x3c00
	s_add_i32 s49, s49, 1
	s_add_i32 s37, s37, s21
	s_mulk_i32 s20, 0x3c00
	s_add_u32 s20, s30, s20
	s_addc_u32 s21, s53, s37
	s_lshl_b64 s[42:43], s[42:43], 1
	s_add_u32 s42, s62, s42
	s_addc_u32 s43, s63, s43
	s_lshl_b32 s37, s64, 14
	s_add_i32 s39, s37, 0xffffc000
	s_cmp_lg_u32 s64, 0
	s_cselect_b32 s39, s39, 0x8000
	v_lshl_add_u64 v[88:89], v[176:177], 1, s[20:21]
	s_mov_b64 s[4:5], 0x400
	s_add_i32 s39, s59, s39
	v_lshl_add_u64 v[88:89], v[88:89], 0, s[4:5]
	s_mov_b32 m0, s39
	s_nop 0
	global_load_lds_dwordx4 v[88:89], off
	v_lshl_add_u64 v[88:89], v[160:161], 1, s[42:43]
	s_add_i32 m0, s39, 0xc000
	s_nop 0
	global_load_lds_dwordx4 v[88:89], off
	v_lshl_add_u64 v[88:89], v[162:163], 1, s[20:21]
	v_lshl_add_u64 v[88:89], v[88:89], 0, s[4:5]
	s_add_i32 m0, s39, 0x400
	s_add_i32 s20, s37, 0
	global_load_lds_dwordx4 v[88:89], off
	v_lshl_add_u64 v[88:89], v[164:165], 1, s[42:43]
	s_add_i32 m0, s39, 0xc400
	s_add_i32 s20, s46, s20
	global_load_lds_dwordx4 v[88:89], off
	v_add3_u32 v100, s20, v211, v166
	v_add3_u32 v116, s20, v210, v166
	ds_read_b128 v[88:91], v100
	ds_read_b128 v[92:95], v100 offset:2048
	ds_read_b128 v[96:99], v100 offset:4096
	ds_read_b128 v[100:103], v100 offset:6144
	ds_read_b128 v[104:107], v116
	ds_read_b128 v[108:111], v116 offset:2048
	ds_read_b128 v[112:115], v116 offset:4096
	ds_read_b128 v[116:119], v116 offset:6144
	s_waitcnt lgkmcnt(0)
	v_mfma_f32_16x16x32_bf16 v[120:123], v[88:91], v[4:7], v[16:19]
	v_mfma_f32_16x16x32_bf16 v[88:91], v[88:91], v[12:15], v[20:23]
	v_mfma_f32_16x16x32_bf16 v[124:127], v[92:95], v[4:7], v[16:19]
	v_mfma_f32_16x16x32_bf16 v[92:95], v[92:95], v[12:15], v[20:23]
	v_mfma_f32_16x16x32_bf16 v[128:131], v[96:99], v[4:7], v[16:19]
	v_mfma_f32_16x16x32_bf16 v[96:99], v[96:99], v[12:15], v[20:23]
	v_mfma_f32_16x16x32_bf16 v[132:135], v[100:103], v[4:7], v[16:19]
	v_mfma_f32_16x16x32_bf16 v[100:103], v[100:103], v[12:15], v[20:23]
	v_mfma_f32_16x16x32_bf16 v[172:175], v[104:107], v[8:11], v[88:91]
	s_nop 2
	v_add_u32_e32 v88, s37, v167
	v_mfma_f32_16x16x32_bf16 v[212:215], v[108:111], v[8:11], v[92:95]
	v_add_u32_e32 v89, v88, v211
	ds_read_b128 v[152:155], v89 offset:49152
	s_nop 0
	v_add_u32_e32 v92, v88, v210
	v_mfma_f32_16x16x32_bf16 v[168:171], v[104:107], v[0:3], v[120:123]
	v_mfma_f32_16x16x32_bf16 v[104:107], v[108:111], v[0:3], v[124:127]
	v_mfma_f32_16x16x32_bf16 v[216:219], v[112:115], v[0:3], v[128:131]
	v_mfma_f32_16x16x32_bf16 v[220:223], v[112:115], v[8:11], v[96:99]
	v_mfma_f32_16x16x32_bf16 v[224:227], v[116:119], v[0:3], v[132:135]
	v_mfma_f32_16x16x32_bf16 v[228:231], v[116:119], v[8:11], v[100:103]
	ds_read_b128 v[112:115], v92 offset:49152
	ds_read_b128 v[116:119], v89 offset:51200
	ds_read_b128 v[120:123], v92 offset:51200
	ds_read_b128 v[128:131], v89 offset:53248
	ds_read_b128 v[124:127], v92 offset:53248
	ds_read_b128 v[132:135], v89 offset:55296
	ds_read_b128 v[136:139], v92 offset:55296
	ds_read_b128 v[144:147], v89 offset:57344
	ds_read_b128 v[140:143], v92 offset:57344
	ds_read_b128 v[156:159], v89 offset:59392
	ds_read_b128 v[148:151], v92 offset:59392
	ds_read_b128 v[108:111], v89 offset:61440
	ds_read_b128 v[96:99], v92 offset:61440
	ds_read_b128 v[88:91], v89 offset:63488
	ds_read_b128 v[92:95], v92 offset:63488
	v_exp_f32_e32 v233, v168
	v_exp_f32_e32 v232, v172
	v_exp_f32_e32 v235, v104
	v_exp_f32_e32 v237, v216
	v_exp_f32_e32 v239, v224
	v_exp_f32_e32 v169, v169
	v_exp_f32_e32 v234, v212
	v_exp_f32_e32 v236, v220
	v_exp_f32_e32 v238, v228
	v_exp_f32_e32 v168, v173
	v_exp_f32_e32 v241, v105
	v_exp_f32_e32 v217, v217
	v_exp_f32_e32 v225, v225
	v_exp_f32_e32 v243, v170
	v_exp_f32_e32 v240, v213
	v_exp_f32_e32 v216, v221
	v_exp_f32_e32 v224, v229
	v_exp_f32_e32 v242, v174
	v_exp_f32_e32 v245, v106
	v_exp_f32_e32 v247, v218
	v_exp_f32_e32 v249, v226
	v_exp_f32_e32 v171, v171
	v_exp_f32_e32 v251, v107
	v_exp_f32_e32 v244, v214
	v_exp_f32_e32 v246, v222
	v_exp_f32_e32 v248, v230
	v_exp_f32_e32 v170, v175
	v_exp_f32_e32 v250, v215
	v_exp_f32_e32 v219, v219
	v_exp_f32_e32 v227, v227
	v_exp_f32_e32 v218, v223
	v_exp_f32_e32 v226, v231
	v_add_f32_e32 v172, 0, v232
	v_add_f32_e32 v173, 0, v233
	v_add_f32_e32 v174, 0, v234
	v_add_f32_e32 v175, 0, v235
	v_add_f32_e32 v212, 0, v236
	v_add_f32_e32 v213, 0, v237
	v_add_f32_e32 v214, 0, v238
	v_add_f32_e32 v215, 0, v239
	v_add_f32_e32 v172, v168, v172
	v_add_f32_e32 v173, v169, v173
	v_add_f32_e32 v174, v240, v174
	v_add_f32_e32 v175, v241, v175
	v_add_f32_e32 v212, v216, v212
	v_add_f32_e32 v213, v217, v213
	v_add_f32_e32 v214, v224, v214
	v_add_f32_e32 v215, v225, v215
	v_add_f32_e32 v172, v242, v172
	v_add_f32_e32 v173, v243, v173
	v_cvt_pk_bf16_f32 v104, v233, v169
	v_cvt_pk_bf16_f32 v105, v243, v171
	v_cvt_pk_bf16_f32 v106, v235, v241
	v_cvt_pk_bf16_f32 v107, v245, v251
	v_add_f32_e32 v174, v244, v174
	v_add_f32_e32 v175, v245, v175
	v_add_f32_e32 v212, v246, v212
	v_add_f32_e32 v213, v247, v213
	v_add_f32_e32 v214, v248, v214
	v_add_f32_e32 v215, v249, v215
	v_add_f32_e32 v172, v170, v172
	v_add_f32_e32 v173, v171, v173
	v_cvt_pk_bf16_f32 v168, v232, v168
	v_cvt_pk_bf16_f32 v169, v242, v170
	v_cvt_pk_bf16_f32 v170, v234, v240
	v_cvt_pk_bf16_f32 v171, v244, v250
	v_add_f32_e32 v174, v250, v174
	v_add_f32_e32 v175, v251, v175
	v_add_f32_e32 v212, v218, v212
	v_add_f32_e32 v213, v219, v213
	v_add_f32_e32 v214, v226, v214
	v_add_f32_e32 v215, v227, v215
	s_waitcnt lgkmcnt(0)
	v_mfma_f32_16x16x32_bf16 v[84:87], v[152:155], v[104:107], v[84:87]
	v_add_f32_e64 v172, v172, v174
	v_add_f32_e64 v173, v173, v175
	v_add_f32_e32 v174, v212, v214
	v_add_f32_e32 v175, v213, v215
	v_cvt_pk_bf16_f32 v100, v237, v217
	v_mfma_f32_16x16x32_bf16 v[80:83], v[152:155], v[168:171], v[80:83]
	v_add_f32_e64 v172, v172, v174
	v_add_f32_e64 v173, v173, v175
	v_cvt_pk_bf16_f32 v101, v247, v219
	v_cvt_pk_bf16_f32 v102, v239, v225
	v_mfma_f32_16x16x32_bf16 v[76:79], v[116:119], v[104:107], v[76:79]
	v_cvt_pk_bf16_f32 v103, v249, v227
	v_add_f32_e32 v182, v182, v172
	v_add_f32_e32 v183, v183, v173
	v_cvt_pk_bf16_f32 v172, v236, v216
	v_mfma_f32_16x16x32_bf16 v[72:75], v[116:119], v[168:171], v[72:75]
	v_cvt_pk_bf16_f32 v173, v246, v218
	v_cvt_pk_bf16_f32 v174, v238, v224
	v_cvt_pk_bf16_f32 v175, v248, v226
	v_mfma_f32_16x16x32_bf16 v[68:71], v[128:131], v[104:107], v[68:71]
	s_add_i32 s20, s64, 1
	s_cmp_lg_u32 s64, 2
	s_cselect_b32 s64, s20, 0
	v_mfma_f32_16x16x32_bf16 v[64:67], v[128:131], v[168:171], v[64:67]
	s_add_u32 s40, s40, 64
	s_addc_u32 s41, s41, 0
	s_cmp_eq_u32 s49, 34
	v_mfma_f32_16x16x32_bf16 v[60:63], v[132:135], v[104:107], v[60:63]
	v_mfma_f32_16x16x32_bf16 v[56:59], v[132:135], v[168:171], v[56:59]
	v_mfma_f32_16x16x32_bf16 v[52:55], v[144:147], v[104:107], v[52:55]
	v_mfma_f32_16x16x32_bf16 v[48:51], v[144:147], v[168:171], v[48:51]
	v_mfma_f32_16x16x32_bf16 v[44:47], v[156:159], v[104:107], v[44:47]
	v_mfma_f32_16x16x32_bf16 v[40:43], v[156:159], v[168:171], v[40:43]
	v_mfma_f32_16x16x32_bf16 v[36:39], v[108:111], v[104:107], v[36:39]
	v_mfma_f32_16x16x32_bf16 v[24:27], v[108:111], v[168:171], v[24:27]
	v_mfma_f32_16x16x32_bf16 v[32:35], v[88:91], v[104:107], v[32:35]
	v_mfma_f32_16x16x32_bf16 v[28:31], v[88:91], v[168:171], v[28:31]
	v_mfma_f32_16x16x32_bf16 v[84:87], v[112:115], v[100:103], v[84:87]
	v_mfma_f32_16x16x32_bf16 v[80:83], v[112:115], v[172:175], v[80:83]
	v_mfma_f32_16x16x32_bf16 v[76:79], v[120:123], v[100:103], v[76:79]
	v_mfma_f32_16x16x32_bf16 v[72:75], v[120:123], v[172:175], v[72:75]
	v_mfma_f32_16x16x32_bf16 v[68:71], v[124:127], v[100:103], v[68:71]
	v_mfma_f32_16x16x32_bf16 v[64:67], v[124:127], v[172:175], v[64:67]
	v_mfma_f32_16x16x32_bf16 v[60:63], v[136:139], v[100:103], v[60:63]
	v_mfma_f32_16x16x32_bf16 v[56:59], v[136:139], v[172:175], v[56:59]
	v_mfma_f32_16x16x32_bf16 v[52:55], v[140:143], v[100:103], v[52:55]
	v_mfma_f32_16x16x32_bf16 v[48:51], v[140:143], v[172:175], v[48:51]
	v_mfma_f32_16x16x32_bf16 v[44:47], v[148:151], v[100:103], v[44:47]
	v_mfma_f32_16x16x32_bf16 v[40:43], v[148:151], v[172:175], v[40:43]
	v_mfma_f32_16x16x32_bf16 v[36:39], v[96:99], v[100:103], v[36:39]
	v_mfma_f32_16x16x32_bf16 v[24:27], v[96:99], v[172:175], v[24:27]
	v_mfma_f32_16x16x32_bf16 v[32:35], v[92:95], v[100:103], v[32:35]
	v_mfma_f32_16x16x32_bf16 v[28:31], v[92:95], v[172:175], v[28:31]
	s_cbranch_scc1 .LBB0_754
